# s5_prompt gelu epilogue: the two constant multiplies (1.5957.. then -log2e) folded into one (30 sites), on top of v23
# baseline (speedup 1.0000x reference)
; #define LAS __attribute__((address_space(3)))
; __device__ __forceinline__ unsigned cvt_pk_bf16(float lo, float hi) { unsigned r; asm("v_cvt_pk_bf16_f32 %0, %1, %2" : "=v"(r) : "v"(lo), "v"(hi)); return r; }
; __device__ __forceinline__ float fgelu(float x) { return x * fsigmoid(1.5957691216057308f * (x + 0.044715f * x * x * x)); }
; #define MFMA32(a, b, c) __builtin_amdgcn_mfma_f32_32x32x16_bf16((a), (b), (c), 0, 0, 0)
; __device__ __forceinline__ void s5_prompt(const Args& a, LAS unsigned char* lds, int b, int g, int tid, int lane, int wave) {
;     ...
;         for (int kq = 0; kq < 8; ++kq) {
; #pragma unroll
;             for (int n = 0; n < 2; ++n) { const bf16x8 bf = *(const LAS bf16x8*)(ZS + (32 * (n0 + n) + r32) * S5_PITCH + 32 * kq + 16 * hh); acc[n] = MFMA32(am[16 + kq], bf, acc[n]); }
;         }
; #pragma unroll
;         for (int n = 0; n < 2; ++n)
; #pragma unroll
;             for (int q = 0; q < 4; ++q) {
;                 const int s = 2 * mt + (q >> 1), c0 = 8 * (q & 1) + 4 * hh, t = 16 * (32 * (n0 + n) + r32) + s;
;                 u32x2 w; w.x = cvt_pk_bf16(fgelu(acc[n][4 * q]), fgelu(acc[n][4 * q + 1])); w.y = cvt_pk_bf16(fgelu(acc[n][4 * q + 2]), fgelu(acc[n][4 * q + 3]));
;                 *(u32x2*)(GS5 + (size_t)(b * SEQ + t) * DH + 16 * g + c0) = w;
;             }
.LBB0_593:
	v_add_u32_e32 v46, v196, v34
	ds_read_b128 v[38:41], v46
	ds_read_b128 v[42:45], v46 offset:32
	v_add_u32_e32 v47, v196, v36
	s_mov_b64 s[36:37], 0
	s_andn2_b64 vcc, exec, s[6:7]
	s_waitcnt vmcnt(7) lgkmcnt(1)
	v_mfma_f32_32x32x16_bf16 v[2:17], v[130:133], v[38:41], v[2:17]
	ds_read_b128 v[34:37], v47
	ds_read_b128 v[38:41], v47 offset:32
	s_waitcnt lgkmcnt(1)
	v_mfma_f32_32x32x16_bf16 v[18:33], v[130:133], v[34:37], v[18:33]
	ds_read_b128 v[34:37], v46 offset:64
	s_waitcnt vmcnt(6)
	v_mfma_f32_32x32x16_bf16 v[2:17], v[134:137], v[42:45], v[2:17]
	s_waitcnt lgkmcnt(1)
	v_mfma_f32_32x32x16_bf16 v[18:33], v[134:137], v[38:41], v[18:33]
	s_waitcnt vmcnt(5) lgkmcnt(0)
	v_mfma_f32_32x32x16_bf16 v[2:17], v[138:141], v[34:37], v[2:17]
	ds_read_b128 v[34:37], v47 offset:64
	s_waitcnt lgkmcnt(0)
	v_mfma_f32_32x32x16_bf16 v[18:33], v[138:141], v[34:37], v[18:33]
	ds_read_b128 v[34:37], v46 offset:96
	s_waitcnt vmcnt(4) lgkmcnt(0)
	v_mfma_f32_32x32x16_bf16 v[2:17], v[142:145], v[34:37], v[2:17]
	ds_read_b128 v[34:37], v47 offset:96
	s_waitcnt lgkmcnt(0)
	v_mfma_f32_32x32x16_bf16 v[18:33], v[142:145], v[34:37], v[18:33]
	ds_read_b128 v[34:37], v46 offset:128
	s_waitcnt vmcnt(3) lgkmcnt(0)
	v_mfma_f32_32x32x16_bf16 v[2:17], v[146:149], v[34:37], v[2:17]
	ds_read_b128 v[34:37], v47 offset:128
	s_waitcnt lgkmcnt(0)
	v_mfma_f32_32x32x16_bf16 v[18:33], v[146:149], v[34:37], v[18:33]
	ds_read_b128 v[34:37], v46 offset:160
	s_waitcnt vmcnt(2) lgkmcnt(0)
	v_mfma_f32_32x32x16_bf16 v[2:17], v[150:153], v[34:37], v[2:17]
	ds_read_b128 v[34:37], v47 offset:160
	s_waitcnt lgkmcnt(0)
	v_mfma_f32_32x32x16_bf16 v[18:33], v[150:153], v[34:37], v[18:33]
	ds_read_b128 v[34:37], v46 offset:192
	s_waitcnt vmcnt(1) lgkmcnt(0)
	v_mfma_f32_32x32x16_bf16 v[2:17], v[154:157], v[34:37], v[2:17]
	ds_read_b128 v[34:37], v47 offset:192
	s_waitcnt lgkmcnt(0)
	v_mfma_f32_32x32x16_bf16 v[18:33], v[154:157], v[34:37], v[18:33]
	ds_read_b128 v[34:37], v46 offset:224
	s_waitcnt vmcnt(0) lgkmcnt(0)
	v_mfma_f32_32x32x16_bf16 v[2:17], v[158:161], v[34:37], v[2:17]
	ds_read_b128 v[34:37], v47 offset:224
	s_waitcnt lgkmcnt(0)
	v_mfma_f32_32x32x16_bf16 v[18:33], v[158:161], v[34:37], v[18:33]
	s_nop 8
	v_mul_f32_e32 v35, 0x3d372713, v2
	v_mul_f32_e32 v35, v2, v35
	v_fma_f32 v35, v2, v35, v2
	v_mul_f32_e32 v35, 0xc0135761, v35
	s_nop 0
	v_exp_f32_e32 v35, v35
	v_lshl_add_u32 v36, s78, 1, v213
	v_lshl_add_u32 v34, s44, 10, v36
	s_mov_b32 s44, 1
	v_add_f32_e32 v35, 1.0, v35
	v_rcp_f32_e32 v35, v35
	s_nop 0
	v_mul_f32_e32 v2, v2, v35
	v_mul_f32_e32 v35, 0x3d372713, v3
	v_mul_f32_e32 v35, v3, v35
	v_fma_f32 v35, v3, v35, v3
	v_mul_f32_e32 v35, 0xc0135761, v35
	s_nop 0
	v_exp_f32_e32 v35, v35
	s_nop 0
	v_add_f32_e32 v35, 1.0, v35
	v_rcp_f32_e32 v35, v35
	s_nop 0
	v_mul_f32_e32 v3, v3, v35
	v_cvt_pk_bf16_f32 v38, v2, v3
	v_mul_f32_e32 v2, 0x3d372713, v4
	v_mul_f32_e32 v3, 0x3d372713, v5
	v_mul_f32_e32 v2, v4, v2
	v_mul_f32_e32 v3, v5, v3
	v_fma_f32 v2, v4, v2, v4
	v_fma_f32 v3, v5, v3, v5
	v_mul_f32_e32 v2, 0xc0135761, v2
	v_mul_f32_e32 v3, 0xc0135761, v3
	s_nop 0
	s_nop 0
	v_exp_f32_e32 v2, v2
	v_exp_f32_e32 v3, v3
	v_ashrrev_i32_e32 v35, 31, v34
	v_add_f32_e32 v2, 1.0, v2
	v_add_f32_e32 v3, 1.0, v3
	v_rcp_f32_e32 v2, v2
	v_rcp_f32_e32 v3, v3
	v_mul_f32_e32 v2, v4, v2
	v_mul_f32_e32 v3, v5, v3
	v_mul_f32_e32 v4, 0x3d372713, v6
	v_mul_f32_e32 v5, 0x3d372713, v7
	v_mul_f32_e32 v4, v6, v4
	v_mul_f32_e32 v5, v7, v5
	v_fma_f32 v4, v6, v4, v6
	v_fma_f32 v5, v7, v5, v7
	v_mul_f32_e32 v4, 0xc0135761, v4
	v_mul_f32_e32 v5, 0xc0135761, v5
	s_nop 0
	s_nop 0
	v_exp_f32_e32 v4, v4
	v_exp_f32_e32 v5, v5
	v_cvt_pk_bf16_f32 v39, v2, v3
	v_lshlrev_b64 v[2:3], 11, v[34:35]
	v_add_f32_e32 v4, 1.0, v4
	v_add_f32_e32 v5, 1.0, v5
	v_rcp_f32_e32 v4, v4
	v_rcp_f32_e32 v5, v5
	v_lshl_add_u64 v[2:3], v[180:181], 0, v[2:3]
	global_store_dwordx2 v[2:3], v[38:39], off
	v_mul_f32_e32 v4, v6, v4
	v_mul_f32_e32 v5, v7, v5
	v_cvt_pk_bf16_f32 v4, v4, v5
	v_mul_f32_e32 v5, 0x3d372713, v8
	v_mul_f32_e32 v5, v8, v5
	v_mul_f32_e32 v6, 0x3d372713, v9
	v_fma_f32 v5, v8, v5, v8
	v_mul_f32_e32 v6, v9, v6
	v_mul_f32_e32 v5, 0xc0135761, v5
	v_fma_f32 v6, v9, v6, v9
	s_nop 0
	v_mul_f32_e32 v6, 0xc0135761, v6
	v_exp_f32_e32 v5, v5
	s_nop 0
	v_exp_f32_e32 v6, v6
	v_add_f32_e32 v5, 1.0, v5
	v_rcp_f32_e32 v5, v5
	v_add_f32_e32 v6, 1.0, v6
	v_rcp_f32_e32 v6, v6
	v_mul_f32_e32 v5, v8, v5
	v_mul_f32_e32 v6, v9, v6
	v_cvt_pk_bf16_f32 v5, v5, v6
	global_store_dwordx2 v[2:3], v[4:5], off offset:16
	v_mul_f32_e32 v2, 0x3d372713, v10
	v_mul_f32_e32 v3, 0x3d372713, v11
	v_mul_f32_e32 v2, v10, v2
	v_mul_f32_e32 v3, v11, v3
	v_fma_f32 v2, v10, v2, v10
	v_fma_f32 v3, v11, v3, v11
	v_mul_f32_e32 v2, 0xc0135761, v2
	v_mul_f32_e32 v3, 0xc0135761, v3
	s_nop 0
	s_nop 0
	v_exp_f32_e32 v2, v2
	v_exp_f32_e32 v3, v3
	v_mul_f32_e32 v4, 0x3d372713, v13
	v_mul_f32_e32 v4, v13, v4
	v_add_f32_e32 v2, 1.0, v2
	v_add_f32_e32 v3, 1.0, v3
	v_rcp_f32_e32 v2, v2
	v_rcp_f32_e32 v3, v3
	v_fma_f32 v4, v13, v4, v13
	v_mul_f32_e32 v4, 0xc0135761, v4
	v_mul_f32_e32 v2, v10, v2
	v_mul_f32_e32 v3, v11, v3
	v_cvt_pk_bf16_f32 v2, v2, v3
	v_mul_f32_e32 v3, 0x3d372713, v12
	v_mul_f32_e32 v3, v12, v3
	v_fma_f32 v3, v12, v3, v12
	v_mul_f32_e32 v3, 0xc0135761, v3
	s_nop 0
	s_nop 0
	v_exp_f32_e32 v3, v3
	v_exp_f32_e32 v4, v4
	v_mul_f32_e32 v6, 0x3d372713, v17
	v_mul_f32_e32 v6, v17, v6
	v_add_f32_e32 v3, 1.0, v3
	v_add_f32_e32 v4, 1.0, v4
	v_rcp_f32_e32 v3, v3
	v_rcp_f32_e32 v4, v4
	v_fma_f32 v6, v17, v6, v17
	v_mul_f32_e32 v6, 0x3fcc422a, v6
	v_mul_f32_e32 v3, v12, v3
	v_mul_f32_e32 v4, v13, v4
	v_cvt_pk_bf16_f32 v3, v3, v4
; __device__ __forceinline__ unsigned cvt_pk_bf16(float lo, float hi) { unsigned r; asm("v_cvt_pk_bf16_f32 %0, %1, %2" : "=v"(r) : "v"(lo), "v"(hi)); return r; }
; __device__ __forceinline__ float fgelu(float x) { return x * fsigmoid(1.5957691216057308f * (x + 0.044715f * x * x * x)); }
; __device__ __forceinline__ void s5_prompt(const Args& a, LAS unsigned char* lds, int b, int g, int tid, int lane, int wave) {
;     ...
; #pragma unroll
;         for (int n = 0; n < 2; ++n)
; #pragma unroll
;             for (int q = 0; q < 4; ++q) {
;                 const int s = 2 * mt + (q >> 1), c0 = 8 * (q & 1) + 4 * hh, t = 16 * (32 * (n0 + n) + r32) + s;
;                 u32x2 w; w.x = cvt_pk_bf16(fgelu(acc[n][4 * q]), fgelu(acc[n][4 * q + 1])); w.y = cvt_pk_bf16(fgelu(acc[n][4 * q + 2]), fgelu(acc[n][4 * q + 3]));
;                 *(u32x2*)(GS5 + (size_t)(b * SEQ + t) * DH + 16 * g + c0) = w;
;             }
	v_or_b32_e32 v4, 1, v34
	v_ashrrev_i32_e32 v5, 31, v4
	v_lshlrev_b64 v[4:5], 11, v[4:5]
	v_lshl_add_u64 v[4:5], v[180:181], 0, v[4:5]
	global_store_dwordx2 v[4:5], v[2:3], off
	v_mul_f32_e32 v2, 0x3d372713, v14
	v_mul_f32_e32 v3, 0x3d372713, v15
	v_mul_f32_e32 v2, v14, v2
	v_mul_f32_e32 v3, v15, v3
	v_fma_f32 v2, v14, v2, v14
	v_fma_f32 v3, v15, v3, v15
	v_mul_f32_e32 v2, 0xc0135761, v2
	v_mul_f32_e32 v3, 0xc0135761, v3
	s_nop 0
	s_nop 0
	v_exp_f32_e32 v2, v2
	v_exp_f32_e32 v3, v3
	v_mul_f32_e32 v6, 0xbfb8aa3b, v6
	v_exp_f32_e32 v6, v6
	v_add_f32_e32 v2, 1.0, v2
	v_add_f32_e32 v3, 1.0, v3
	v_rcp_f32_e32 v2, v2
	v_rcp_f32_e32 v3, v3
	v_add_f32_e32 v6, 1.0, v6
	v_rcp_f32_e32 v6, v6
	v_mul_f32_e32 v2, v14, v2
	v_mul_f32_e32 v3, v15, v3
	v_cvt_pk_bf16_f32 v2, v2, v3
	v_mul_f32_e32 v3, 0x3d372713, v16
	v_mul_f32_e32 v3, v16, v3
	v_fma_f32 v3, v16, v3, v16
	v_mul_f32_e32 v3, 0xc0135761, v3
	s_nop 0
	v_exp_f32_e32 v3, v3
	v_mul_f32_e32 v6, v17, v6
	v_add_f32_e32 v3, 1.0, v3
	v_rcp_f32_e32 v3, v3
	s_nop 0
	v_mul_f32_e32 v3, v16, v3
	v_cvt_pk_bf16_f32 v3, v3, v6
	global_store_dwordx2 v[4:5], v[2:3], off offset:16
	v_mul_f32_e32 v3, 0x3d372713, v18
	v_mul_f32_e32 v4, 0x3d372713, v19
	v_mul_f32_e32 v3, v18, v3
	v_mul_f32_e32 v4, v19, v4
	v_fma_f32 v3, v18, v3, v18
	v_fma_f32 v4, v19, v4, v19
	v_mul_f32_e32 v3, 0xc0135761, v3
	v_mul_f32_e32 v4, 0xc0135761, v4
	s_nop 0
	s_nop 0
	v_exp_f32_e32 v3, v3
	v_exp_f32_e32 v4, v4
	v_mul_f32_e32 v5, 0x3d372713, v21
	v_mul_f32_e32 v5, v21, v5
	v_add_f32_e32 v3, 1.0, v3
	v_add_f32_e32 v4, 1.0, v4
	v_rcp_f32_e32 v3, v3
	v_rcp_f32_e32 v4, v4
	v_fma_f32 v5, v21, v5, v21
	v_mul_f32_e32 v5, 0xc0135761, v5
	v_mul_f32_e32 v3, v18, v3
	v_mul_f32_e32 v4, v19, v4
	v_cvt_pk_bf16_f32 v4, v3, v4
	v_mul_f32_e32 v3, 0x3d372713, v20
	v_mul_f32_e32 v3, v20, v3
	v_fma_f32 v3, v20, v3, v20
	v_mul_f32_e32 v3, 0xc0135761, v3
	s_nop 0
	s_nop 0
	v_exp_f32_e32 v3, v3
	v_exp_f32_e32 v5, v5
	v_lshl_add_u32 v2, s76, 9, v36
	s_mov_b64 s[76:77], -1
	v_add_f32_e32 v3, 1.0, v3
	v_add_f32_e32 v5, 1.0, v5
	v_rcp_f32_e32 v3, v3
	v_rcp_f32_e32 v5, v5
	v_mul_f32_e32 v3, v20, v3
	v_mul_f32_e32 v5, v21, v5
	v_cvt_pk_bf16_f32 v5, v3, v5
	v_ashrrev_i32_e32 v3, 31, v2
	v_lshlrev_b64 v[6:7], 11, v[2:3]
	v_lshl_add_u64 v[6:7], v[180:181], 0, v[6:7]
	global_store_dwordx2 v[6:7], v[4:5], off
	v_mul_f32_e32 v3, 0x3d372713, v22
	v_mul_f32_e32 v4, 0x3d372713, v23
	v_mul_f32_e32 v3, v22, v3
	v_mul_f32_e32 v4, v23, v4
	v_fma_f32 v3, v22, v3, v22
	v_fma_f32 v4, v23, v4, v23
	v_mul_f32_e32 v3, 0xc0135761, v3
	v_mul_f32_e32 v4, 0xc0135761, v4
	s_nop 0
	s_nop 0
	v_exp_f32_e32 v3, v3
	v_exp_f32_e32 v4, v4
	v_mul_f32_e32 v5, 0x3d372713, v25
	v_mul_f32_e32 v5, v25, v5
	v_add_f32_e32 v3, 1.0, v3
	v_add_f32_e32 v4, 1.0, v4
	v_rcp_f32_e32 v3, v3
	v_rcp_f32_e32 v4, v4
	v_fma_f32 v5, v25, v5, v25
	v_mul_f32_e32 v5, 0xc0135761, v5
	v_mul_f32_e32 v3, v22, v3
	v_mul_f32_e32 v4, v23, v4
	v_cvt_pk_bf16_f32 v4, v3, v4
	v_mul_f32_e32 v3, 0x3d372713, v24
	v_mul_f32_e32 v3, v24, v3
	v_fma_f32 v3, v24, v3, v24
	v_mul_f32_e32 v3, 0xc0135761, v3
	s_nop 0
	s_nop 0
	v_exp_f32_e32 v3, v3
	v_exp_f32_e32 v5, v5
	v_or_b32_e32 v2, 1, v2
	v_add_f32_e32 v3, 1.0, v3
	v_add_f32_e32 v5, 1.0, v5
	v_rcp_f32_e32 v3, v3
	v_rcp_f32_e32 v5, v5
	v_mul_f32_e32 v3, v24, v3
	v_mul_f32_e32 v5, v25, v5
	v_cvt_pk_bf16_f32 v5, v3, v5
	global_store_dwordx2 v[6:7], v[4:5], off offset:16
	v_mul_f32_e32 v3, 0x3d372713, v26
	v_mul_f32_e32 v4, 0x3d372713, v27
	v_mul_f32_e32 v3, v26, v3
	v_mul_f32_e32 v4, v27, v4
	v_fma_f32 v3, v26, v3, v26
	v_fma_f32 v4, v27, v4, v27
	v_mul_f32_e32 v3, 0xc0135761, v3
	v_mul_f32_e32 v4, 0xc0135761, v4
	s_nop 0
	s_nop 0
	v_exp_f32_e32 v3, v3
	v_exp_f32_e32 v4, v4
	v_mul_f32_e32 v5, 0x3d372713, v29
	v_mul_f32_e32 v5, v29, v5
	v_add_f32_e32 v3, 1.0, v3
	v_add_f32_e32 v4, 1.0, v4
	v_rcp_f32_e32 v3, v3
	v_rcp_f32_e32 v4, v4
	v_fma_f32 v5, v29, v5, v29
	v_mul_f32_e32 v5, 0xc0135761, v5
	v_mul_f32_e32 v3, v26, v3
	v_mul_f32_e32 v4, v27, v4
	v_cvt_pk_bf16_f32 v4, v3, v4
	v_mul_f32_e32 v3, 0x3d372713, v28
	v_mul_f32_e32 v3, v28, v3
	v_fma_f32 v3, v28, v3, v28
	v_mul_f32_e32 v3, 0xc0135761, v3
	s_nop 0
	s_nop 0
	v_exp_f32_e32 v3, v3
	v_exp_f32_e32 v5, v5
	v_mul_f32_e32 v6, 0x3d372713, v33
	v_mul_f32_e32 v6, v33, v6
	v_add_f32_e32 v3, 1.0, v3
	v_add_f32_e32 v5, 1.0, v5
	v_rcp_f32_e32 v3, v3
	v_rcp_f32_e32 v5, v5
	v_fma_f32 v6, v33, v6, v33
	v_mul_f32_e32 v6, 0x3fcc422a, v6
	v_mul_f32_e32 v3, v28, v3
	v_mul_f32_e32 v5, v29, v5
	v_cvt_pk_bf16_f32 v5, v3, v5
	v_ashrrev_i32_e32 v3, 31, v2
	v_lshlrev_b64 v[2:3], 11, v[2:3]
	v_lshl_add_u64 v[2:3], v[180:181], 0, v[2:3]
	global_store_dwordx2 v[2:3], v[4:5], off
	v_mul_f32_e32 v4, 0x3d372713, v30
	v_mul_f32_e32 v5, 0x3d372713, v31
	v_mul_f32_e32 v4, v30, v4
	v_mul_f32_e32 v5, v31, v5
	v_fma_f32 v4, v30, v4, v30
	v_fma_f32 v5, v31, v5, v31
	v_mul_f32_e32 v4, 0xc0135761, v4
	v_mul_f32_e32 v5, 0xc0135761, v5
	s_nop 0
	s_nop 0
	v_exp_f32_e32 v4, v4
	v_exp_f32_e32 v5, v5
	v_mul_f32_e32 v6, 0xbfb8aa3b, v6
	v_exp_f32_e32 v6, v6
	v_add_f32_e32 v4, 1.0, v4
	v_add_f32_e32 v5, 1.0, v5
	v_rcp_f32_e32 v4, v4
	v_rcp_f32_e32 v5, v5
	v_add_f32_e32 v6, 1.0, v6
	v_rcp_f32_e32 v6, v6
	v_mul_f32_e32 v4, v30, v4
	v_mul_f32_e32 v5, v31, v5
	v_cvt_pk_bf16_f32 v4, v4, v5
	v_mul_f32_e32 v5, 0x3d372713, v32
	v_mul_f32_e32 v5, v32, v5
	v_fma_f32 v5, v32, v5, v32
	v_mul_f32_e32 v5, 0xc0135761, v5
	s_nop 0
	v_exp_f32_e32 v5, v5
	v_mul_f32_e32 v6, v33, v6
	v_add_f32_e32 v5, 1.0, v5
	v_rcp_f32_e32 v5, v5
	s_nop 0
	v_mul_f32_e32 v5, v32, v5
	v_cvt_pk_bf16_f32 v5, v5, v6
	global_store_dwordx2 v[2:3], v[4:5], off offset:16
	s_cbranch_vccz .LBB0_558
